# early L1 invalidate (right after the arrive atomic) also on the two split barriers inside P2
# baseline (speedup 1.0000x reference)
; __device__ __forceinline__ unsigned xb_ld(unsigned* p)              { return __hip_atomic_load(p, __ATOMIC_RELAXED, __HIP_MEMORY_SCOPE_AGENT); }
; #define XB_SPIN(cond, bar) do { unsigned _sp = 0; while (cond) { __builtin_amdgcn_s_sleep(1); \
;     if ((++_sp & 255u) == 0u) { if (xb_ld(&(bar)[XB_TMO])) break; if (_sp > XB_SPIN_CAP) { atomicAdd(&(bar)[XB_TMO], 1u); break; } } } } while (0)
; __device__ __forceinline__ void xcd_barrier_wait(const XcdBarrier& b) {
;     ...
;         } else {
;             XB_SPIN(xb_ld(&bar[XB_TOPGEN]) == gen, bar);
;             __builtin_amdgcn_fence(__ATOMIC_ACQUIRE, "agent");
;             asm volatile("s_waitcnt vmcnt(0)" ::: "memory");
;         }
;     }
;     __syncthreads();
; __device__ __forceinline__ void hgrn_scan(const float* US, const float* DD, bf16* SB, int gtid, int gstride) {
;     for (int e = gtid; e < 8 * 16384; e += gstride) { const int chain = e >> 14, idx = e & 16383, k = idx & 127; float run = 0.f;
.LBB0_640:
	s_waitcnt vmcnt(0)
	s_waitcnt vmcnt(0)
.LBB0_641:
	s_or_b64 exec, exec, s[0:1]
	s_waitcnt lgkmcnt(1)
	v_mov_b32_e32 v0, v252
	v_readlane_b32 s0, v254, 38
	s_waitcnt lgkmcnt(0)
	s_barrier
	s_mov_b32 s2, 0x20000
	v_add_u32_e32 v8, s0, v0
	s_mov_b64 s[0:1], s[20:21]
	v_cmp_gt_i32_e32 vcc, s2, v8
	s_and_saveexec_b64 s[2:3], vcc
	s_cbranch_execz .LBB0_646
	s_add_u32 s4, s0, 0x1d800000
	v_and_b32_e32 v1, 0x7f, v0
	v_readlane_b32 s8, v254, 38
	s_addc_u32 s5, s1, 0
	v_or_b32_e32 v9, 0x780, v1
	v_add_u16_e32 v10, s8, v0
	s_mov_b64 s[8:9], 0

; __device__ __forceinline__ unsigned xb_add(unsigned* p, unsigned v) { return __hip_atomic_fetch_add(p, v, __ATOMIC_RELAXED, __HIP_MEMORY_SCOPE_AGENT); }
; __device__ __forceinline__ void xcd_barrier_arrive(const XcdBarrier& b) {
;     ...
;         const unsigned old = xb_add(&bar[XB_XSUB(b.x)], 1u);
;         const unsigned gen = old / nloc;
;         unsigned role = 0u, tg = 0u;
;         if (old + 1u == (gen + 1u) * nloc) {
;             __builtin_amdgcn_fence(__ATOMIC_RELEASE, "agent");
;             asm volatile("s_waitcnt vmcnt(0)" ::: "memory");
;             const unsigned og = xb_add(&bar[XB_TOP], 1u);
;             tg = og / nx; role = 1u;
;             if (og + 1u == (tg + 1u) * nx) { xb_add(&bar[XB_TOPGEN], 1u); role = 2u; }
.LBB0_662:
	s_mov_b64 s[4:5], exec
	v_mbcnt_lo_u32_b32 v1, s4, 0
	v_mbcnt_hi_u32_b32 v1, s5, v1
	v_cmp_eq_u32_e32 vcc, 0, v1
	s_and_saveexec_b64 s[2:3], vcc
	s_cbranch_execz .LBB0_664
	s_bcnt1_i32_b64 s4, s[4:5]
	v_mov_b32_e32 v3, s4
	v_readlane_b32 s4, v254, 25
	v_readlane_b32 s5, v254, 26
	s_nop 4
	global_atomic_add v3, v169, v3, s[4:5] sc0
	buffer_inv sc1
.LBB0_664:
	s_or_b64 exec, exec, s[2:3]
	s_waitcnt vmcnt(0)
	v_readfirstlane_b32 s2, v3
	v_sub_u32_e32 v4, 0, v2
	s_nop 0
	v_add_u32_e32 v3, s2, v1
	v_cvt_f32_u32_e32 v1, v2
	v_rcp_iflag_f32_e32 v1, v1
	s_nop 0
	v_mul_f32_e32 v1, 0x4f7ffffe, v1
	v_cvt_u32_f32_e32 v1, v1
	v_mul_lo_u32 v4, v4, v1
	v_mul_hi_u32 v4, v1, v4
	v_add_u32_e32 v1, v1, v4
	v_mul_hi_u32 v1, v3, v1
	v_mul_lo_u32 v4, v1, v2
	v_sub_u32_e32 v4, v3, v4
	v_cmp_ge_u32_e32 vcc, v4, v2
	v_add_u32_e32 v5, 1, v1
	v_add_u32_e32 v3, 1, v3
	v_cndmask_b32_e32 v1, v1, v5, vcc
	v_sub_u32_e32 v5, v4, v2
	v_cndmask_b32_e32 v4, v4, v5, vcc
	v_cmp_ge_u32_e32 vcc, v4, v2
	v_add_u32_e32 v4, 1, v1
	s_nop 0
	v_cndmask_b32_e32 v1, v1, v4, vcc
	v_mul_lo_u32 v4, v2, v1
	v_add_u32_e32 v2, v4, v2
	v_cmp_eq_u32_e32 vcc, v3, v2
	v_mov_b32_e32 v2, 0
	v_mov_b32_e32 v3, 0
	s_and_saveexec_b64 s[2:3], vcc
	s_cbranch_execz .LBB0_672
	s_mov_b64 s[4:5], exec
	buffer_wbl2 sc1
	s_waitcnt lgkmcnt(0)
	s_waitcnt vmcnt(0)
	v_mbcnt_lo_u32_b32 v2, s4, 0
	v_mbcnt_hi_u32_b32 v3, s5, v2
	v_cmp_eq_u32_e32 vcc, 0, v3
	s_and_saveexec_b64 s[8:9], vcc
	s_cbranch_execz .LBB0_667
	s_bcnt1_i32_b64 s4, s[4:5]
	v_mov_b32_e32 v2, s4
	v_readlane_b32 s4, v254, 29
	v_readlane_b32 s5, v254, 30
	s_nop 4
	global_atomic_add v2, v169, v2, s[4:5] sc0
